# hand-scheduled EpiIn epilogue paths: sigmoid-gate tiles (-log2e folded into the row scale, packed f32 add) and plain tiles (row scales read up front, lane transposes overlapped), same f32 op kinds
# speedup vs baseline: 1.0048x; 1.0048x over previous
.LBB0_776:
	s_xor_b64 s[16:17], s[24:25], -1
	s_xor_b64 s[18:19], s[18:19], -1
	s_add_i32 s42, s55, s66
	s_add_u32 s15, s6, s22
	s_addc_u32 s22, s7, s23
	s_ashr_i32 s21, s20, 31
	s_lshl_b64 s[20:21], s[20:21], 1
	s_add_u32 s20, s15, s20
	v_lshl_add_u32 v161, v144, 2, s70
	s_addc_u32 s21, s22, s21
	s_lshl_b32 s15, s14, 1
	s_add_i32 s15, s15, 6
	ds_read_b32 v154, v161
	s_and_b32 s25, s15, 6
	v_ashrrev_i32_e32 v2, 2, v146
	v_and_b32_e32 v147, 3, v144
	v_and_b32_e32 v148, -4, v146
	s_add_i32 s25, s25, s34
	v_lshl_add_u32 v159, v147, 6, v148
	v_add_u32_e32 v160, s42, v2
	v_lshl_or_b32 v2, v147, 4, s82
	s_cmp_gt_i32 s14, 16
	v_lshlrev_b32_e32 v148, 4, v146
	s_mov_b64 s[26:27], -1
	v_lshl_add_u64 v[150:151], s[20:21], 0, v[2:3]
	s_cselect_b32 s24, 0x800, 0
	v_ashrrev_i32_e32 v149, 31, v148
	v_cmp_gt_i32_e64 s[40:41], 2, v145
	s_and_b64 vcc, exec, s[16:17]
	s_cbranch_vccz .LBB0_782
	s_mov_b64 s[14:15], -1
	s_and_b64 vcc, exec, s[18:19]
	s_cbranch_vccz .LBB0_779
	ds_read_b32 v162, v161
	ds_read_b32 v164, v161 offset:64
	ds_read_b32 v166, v161 offset:128
	ds_read_b32 v168, v161 offset:192
	ds_read_b32 v170, v161 offset:512
	ds_read_b32 v172, v161 offset:576
	ds_read_b32 v174, v161 offset:640
	ds_read_b32 v176, v161 offset:704
	v_mul_lo_u32 v194, v160, s62
	v_mov_b32_e32 v195, 0
	s_lshl_b32 s16, s62, 5
	s_mov_b32 s17, 0
	s_mul_i32 s14, s62, 0xa0
	s_mov_b32 s15, 0
	v_lshl_add_u64 v[194:195], v[194:195], 1, v[150:151]
	s_waitcnt lgkmcnt(0)
	v_pk_mul_f32 v[120:121], v[120:121], v[162:163] op_sel_hi:[1,0]
	v_pk_mul_f32 v[122:123], v[122:123], v[162:163] op_sel_hi:[1,0]
	v_pk_mul_f32 v[116:117], v[116:117], v[162:163] op_sel_hi:[1,0]
	v_pk_mul_f32 v[118:119], v[118:119], v[162:163] op_sel_hi:[1,0]
	v_pk_mul_f32 v[128:129], v[128:129], v[162:163] op_sel_hi:[1,0]
	v_pk_mul_f32 v[130:131], v[130:131], v[162:163] op_sel_hi:[1,0]
	v_pk_mul_f32 v[124:125], v[124:125], v[162:163] op_sel_hi:[1,0]
	v_pk_mul_f32 v[126:127], v[126:127], v[162:163] op_sel_hi:[1,0]
	v_cvt_pk_bf16_f32 v178, v120, v121
	v_cvt_pk_bf16_f32 v179, v122, v123
	v_cvt_pk_bf16_f32 v180, v116, v117
	v_cvt_pk_bf16_f32 v181, v118, v119
	v_cvt_pk_bf16_f32 v182, v128, v129
	v_cvt_pk_bf16_f32 v183, v130, v131
	v_cvt_pk_bf16_f32 v184, v124, v125
	v_cvt_pk_bf16_f32 v185, v126, v127
	ds_bpermute_b32 v206, v159, v178
	ds_bpermute_b32 v207, v159, v179
	ds_bpermute_b32 v208, v159, v180
	ds_bpermute_b32 v209, v159, v181
	ds_bpermute_b32 v210, v159, v182
	ds_bpermute_b32 v211, v159, v183
	ds_bpermute_b32 v212, v159, v184
	ds_bpermute_b32 v213, v159, v185
	v_pk_mul_f32 v[104:105], v[104:105], v[164:165] op_sel_hi:[1,0]
	v_pk_mul_f32 v[106:107], v[106:107], v[164:165] op_sel_hi:[1,0]
	v_pk_mul_f32 v[100:101], v[100:101], v[164:165] op_sel_hi:[1,0]
	v_pk_mul_f32 v[102:103], v[102:103], v[164:165] op_sel_hi:[1,0]
	v_pk_mul_f32 v[112:113], v[112:113], v[164:165] op_sel_hi:[1,0]
	v_pk_mul_f32 v[114:115], v[114:115], v[164:165] op_sel_hi:[1,0]
	v_pk_mul_f32 v[108:109], v[108:109], v[164:165] op_sel_hi:[1,0]
	v_pk_mul_f32 v[110:111], v[110:111], v[164:165] op_sel_hi:[1,0]
	v_cvt_pk_bf16_f32 v186, v104, v105
	v_cvt_pk_bf16_f32 v187, v106, v107
	v_cvt_pk_bf16_f32 v188, v100, v101
	v_cvt_pk_bf16_f32 v189, v102, v103
	v_cvt_pk_bf16_f32 v190, v112, v113
	v_cvt_pk_bf16_f32 v191, v114, v115
	v_cvt_pk_bf16_f32 v192, v108, v109
	v_cvt_pk_bf16_f32 v193, v110, v111
	ds_bpermute_b32 v214, v159, v186
	ds_bpermute_b32 v215, v159, v187
	ds_bpermute_b32 v216, v159, v188
	ds_bpermute_b32 v217, v159, v189
	ds_bpermute_b32 v218, v159, v190
	ds_bpermute_b32 v219, v159, v191
	ds_bpermute_b32 v220, v159, v192
	ds_bpermute_b32 v221, v159, v193
	s_waitcnt lgkmcnt(8)
	global_store_dwordx4 v[194:195], v[206:209], off
	global_store_dwordx4 v[194:195], v[210:213], off offset:256
	v_lshl_add_u64 v[194:195], v[194:195], 0, s[16:17]
	v_pk_mul_f32 v[88:89], v[88:89], v[166:167] op_sel_hi:[1,0]
	v_pk_mul_f32 v[90:91], v[90:91], v[166:167] op_sel_hi:[1,0]
	v_pk_mul_f32 v[84:85], v[84:85], v[166:167] op_sel_hi:[1,0]
	v_pk_mul_f32 v[86:87], v[86:87], v[166:167] op_sel_hi:[1,0]
	v_pk_mul_f32 v[96:97], v[96:97], v[166:167] op_sel_hi:[1,0]
	v_pk_mul_f32 v[98:99], v[98:99], v[166:167] op_sel_hi:[1,0]
	v_pk_mul_f32 v[92:93], v[92:93], v[166:167] op_sel_hi:[1,0]
	v_pk_mul_f32 v[94:95], v[94:95], v[166:167] op_sel_hi:[1,0]
	v_cvt_pk_bf16_f32 v178, v88, v89
	v_cvt_pk_bf16_f32 v179, v90, v91
	v_cvt_pk_bf16_f32 v180, v84, v85
	v_cvt_pk_bf16_f32 v181, v86, v87
	v_cvt_pk_bf16_f32 v182, v96, v97
	v_cvt_pk_bf16_f32 v183, v98, v99
	v_cvt_pk_bf16_f32 v184, v92, v93
	v_cvt_pk_bf16_f32 v185, v94, v95
	ds_bpermute_b32 v206, v159, v178
	ds_bpermute_b32 v207, v159, v179
	ds_bpermute_b32 v208, v159, v180
	ds_bpermute_b32 v209, v159, v181
	ds_bpermute_b32 v210, v159, v182
	ds_bpermute_b32 v211, v159, v183
	ds_bpermute_b32 v212, v159, v184
	ds_bpermute_b32 v213, v159, v185
	s_waitcnt lgkmcnt(8)
	global_store_dwordx4 v[194:195], v[214:217], off
	global_store_dwordx4 v[194:195], v[218:221], off offset:256
	v_lshl_add_u64 v[194:195], v[194:195], 0, s[16:17]
	v_pk_mul_f32 v[72:73], v[72:73], v[168:169] op_sel_hi:[1,0]
	v_pk_mul_f32 v[74:75], v[74:75], v[168:169] op_sel_hi:[1,0]
	v_pk_mul_f32 v[68:69], v[68:69], v[168:169] op_sel_hi:[1,0]
	v_pk_mul_f32 v[70:71], v[70:71], v[168:169] op_sel_hi:[1,0]
	v_pk_mul_f32 v[80:81], v[80:81], v[168:169] op_sel_hi:[1,0]
	v_pk_mul_f32 v[82:83], v[82:83], v[168:169] op_sel_hi:[1,0]
	v_pk_mul_f32 v[76:77], v[76:77], v[168:169] op_sel_hi:[1,0]
	v_pk_mul_f32 v[78:79], v[78:79], v[168:169] op_sel_hi:[1,0]
	v_cvt_pk_bf16_f32 v186, v72, v73
	v_cvt_pk_bf16_f32 v187, v74, v75
	v_cvt_pk_bf16_f32 v188, v68, v69
	v_cvt_pk_bf16_f32 v189, v70, v71
	v_cvt_pk_bf16_f32 v190, v80, v81
	v_cvt_pk_bf16_f32 v191, v82, v83
	v_cvt_pk_bf16_f32 v192, v76, v77
	v_cvt_pk_bf16_f32 v193, v78, v79
	ds_bpermute_b32 v214, v159, v186
	ds_bpermute_b32 v215, v159, v187
	ds_bpermute_b32 v216, v159, v188
	ds_bpermute_b32 v217, v159, v189
	ds_bpermute_b32 v218, v159, v190
	ds_bpermute_b32 v219, v159, v191
	ds_bpermute_b32 v220, v159, v192
	ds_bpermute_b32 v221, v159, v193
	s_waitcnt lgkmcnt(8)
	global_store_dwordx4 v[194:195], v[206:209], off
	global_store_dwordx4 v[194:195], v[210:213], off offset:256
	v_lshl_add_u64 v[194:195], v[194:195], 0, s[16:17]
	v_pk_mul_f32 v[56:57], v[56:57], v[170:171] op_sel_hi:[1,0]
	v_pk_mul_f32 v[58:59], v[58:59], v[170:171] op_sel_hi:[1,0]
	v_pk_mul_f32 v[52:53], v[52:53], v[170:171] op_sel_hi:[1,0]
	v_pk_mul_f32 v[54:55], v[54:55], v[170:171] op_sel_hi:[1,0]
	v_pk_mul_f32 v[64:65], v[64:65], v[170:171] op_sel_hi:[1,0]
	v_pk_mul_f32 v[66:67], v[66:67], v[170:171] op_sel_hi:[1,0]
	v_pk_mul_f32 v[60:61], v[60:61], v[170:171] op_sel_hi:[1,0]
	v_pk_mul_f32 v[62:63], v[62:63], v[170:171] op_sel_hi:[1,0]
	v_cvt_pk_bf16_f32 v178, v56, v57
	v_cvt_pk_bf16_f32 v179, v58, v59
	v_cvt_pk_bf16_f32 v180, v52, v53
	v_cvt_pk_bf16_f32 v181, v54, v55
	v_cvt_pk_bf16_f32 v182, v64, v65
	v_cvt_pk_bf16_f32 v183, v66, v67
	v_cvt_pk_bf16_f32 v184, v60, v61
	v_cvt_pk_bf16_f32 v185, v62, v63
	ds_bpermute_b32 v206, v159, v178
	ds_bpermute_b32 v207, v159, v179
	ds_bpermute_b32 v208, v159, v180
	ds_bpermute_b32 v209, v159, v181
	ds_bpermute_b32 v210, v159, v182
	ds_bpermute_b32 v211, v159, v183
	ds_bpermute_b32 v212, v159, v184
	ds_bpermute_b32 v213, v159, v185
	s_waitcnt lgkmcnt(8)
	global_store_dwordx4 v[194:195], v[214:217], off
	global_store_dwordx4 v[194:195], v[218:221], off offset:256
	v_lshl_add_u64 v[194:195], v[194:195], 0, s[14:15]
	v_pk_mul_f32 v[40:41], v[40:41], v[172:173] op_sel_hi:[1,0]
	v_pk_mul_f32 v[42:43], v[42:43], v[172:173] op_sel_hi:[1,0]
	v_pk_mul_f32 v[36:37], v[36:37], v[172:173] op_sel_hi:[1,0]
	v_pk_mul_f32 v[38:39], v[38:39], v[172:173] op_sel_hi:[1,0]
	v_pk_mul_f32 v[48:49], v[48:49], v[172:173] op_sel_hi:[1,0]
	v_pk_mul_f32 v[50:51], v[50:51], v[172:173] op_sel_hi:[1,0]
	v_pk_mul_f32 v[44:45], v[44:45], v[172:173] op_sel_hi:[1,0]
	v_pk_mul_f32 v[46:47], v[46:47], v[172:173] op_sel_hi:[1,0]
	v_cvt_pk_bf16_f32 v186, v40, v41
	v_cvt_pk_bf16_f32 v187, v42, v43
	v_cvt_pk_bf16_f32 v188, v36, v37
	v_cvt_pk_bf16_f32 v189, v38, v39
	v_cvt_pk_bf16_f32 v190, v48, v49
	v_cvt_pk_bf16_f32 v191, v50, v51
	v_cvt_pk_bf16_f32 v192, v44, v45
	v_cvt_pk_bf16_f32 v193, v46, v47
	ds_bpermute_b32 v214, v159, v186
	ds_bpermute_b32 v215, v159, v187
	ds_bpermute_b32 v216, v159, v188
	ds_bpermute_b32 v217, v159, v189
	ds_bpermute_b32 v218, v159, v190
	ds_bpermute_b32 v219, v159, v191
	ds_bpermute_b32 v220, v159, v192
	ds_bpermute_b32 v221, v159, v193
	s_waitcnt lgkmcnt(8)
	global_store_dwordx4 v[194:195], v[206:209], off
	global_store_dwordx4 v[194:195], v[210:213], off offset:256
	v_lshl_add_u64 v[194:195], v[194:195], 0, s[16:17]
	v_pk_mul_f32 v[24:25], v[24:25], v[174:175] op_sel_hi:[1,0]
	v_pk_mul_f32 v[26:27], v[26:27], v[174:175] op_sel_hi:[1,0]
	v_pk_mul_f32 v[20:21], v[20:21], v[174:175] op_sel_hi:[1,0]
	v_pk_mul_f32 v[22:23], v[22:23], v[174:175] op_sel_hi:[1,0]
	v_pk_mul_f32 v[32:33], v[32:33], v[174:175] op_sel_hi:[1,0]
	v_pk_mul_f32 v[34:35], v[34:35], v[174:175] op_sel_hi:[1,0]
	v_pk_mul_f32 v[28:29], v[28:29], v[174:175] op_sel_hi:[1,0]
	v_pk_mul_f32 v[30:31], v[30:31], v[174:175] op_sel_hi:[1,0]
	v_cvt_pk_bf16_f32 v178, v24, v25
	v_cvt_pk_bf16_f32 v179, v26, v27
	v_cvt_pk_bf16_f32 v180, v20, v21
	v_cvt_pk_bf16_f32 v181, v22, v23
	v_cvt_pk_bf16_f32 v182, v32, v33
	v_cvt_pk_bf16_f32 v183, v34, v35
	v_cvt_pk_bf16_f32 v184, v28, v29
	v_cvt_pk_bf16_f32 v185, v30, v31
	ds_bpermute_b32 v206, v159, v178
	ds_bpermute_b32 v207, v159, v179
	ds_bpermute_b32 v208, v159, v180
	ds_bpermute_b32 v209, v159, v181
	ds_bpermute_b32 v210, v159, v182
	ds_bpermute_b32 v211, v159, v183
	ds_bpermute_b32 v212, v159, v184
	ds_bpermute_b32 v213, v159, v185
	s_waitcnt lgkmcnt(8)
	global_store_dwordx4 v[194:195], v[214:217], off
	global_store_dwordx4 v[194:195], v[218:221], off offset:256
	v_lshl_add_u64 v[194:195], v[194:195], 0, s[16:17]
	v_pk_mul_f32 v[8:9], v[8:9], v[176:177] op_sel_hi:[1,0]
	v_pk_mul_f32 v[10:11], v[10:11], v[176:177] op_sel_hi:[1,0]
	v_pk_mul_f32 v[4:5], v[4:5], v[176:177] op_sel_hi:[1,0]
	v_pk_mul_f32 v[6:7], v[6:7], v[176:177] op_sel_hi:[1,0]
	v_pk_mul_f32 v[16:17], v[16:17], v[176:177] op_sel_hi:[1,0]
	v_pk_mul_f32 v[18:19], v[18:19], v[176:177] op_sel_hi:[1,0]
	v_pk_mul_f32 v[12:13], v[12:13], v[176:177] op_sel_hi:[1,0]
	v_pk_mul_f32 v[14:15], v[14:15], v[176:177] op_sel_hi:[1,0]
	v_cvt_pk_bf16_f32 v186, v8, v9
	v_cvt_pk_bf16_f32 v187, v10, v11
	v_cvt_pk_bf16_f32 v188, v4, v5
	v_cvt_pk_bf16_f32 v189, v6, v7
	v_cvt_pk_bf16_f32 v190, v16, v17
	v_cvt_pk_bf16_f32 v191, v18, v19
	v_cvt_pk_bf16_f32 v192, v12, v13
	v_cvt_pk_bf16_f32 v193, v14, v15
	ds_bpermute_b32 v214, v159, v186
	ds_bpermute_b32 v215, v159, v187
	ds_bpermute_b32 v216, v159, v188
	ds_bpermute_b32 v217, v159, v189
	ds_bpermute_b32 v218, v159, v190
	ds_bpermute_b32 v219, v159, v191
	ds_bpermute_b32 v220, v159, v192
	ds_bpermute_b32 v221, v159, v193
	s_waitcnt lgkmcnt(8)
	global_store_dwordx4 v[194:195], v[206:209], off
	global_store_dwordx4 v[194:195], v[210:213], off offset:256
	v_lshl_add_u64 v[194:195], v[194:195], 0, s[16:17]
	s_waitcnt lgkmcnt(0)
	global_store_dwordx4 v[194:195], v[214:217], off
	global_store_dwordx4 v[194:195], v[218:221], off offset:256
	s_branch .LBB0_860
	v_ashrrev_i32_e32 v2, 31, v160
	v_mul_lo_u32 v152, s63, v160
	v_mul_lo_u32 v2, s62, v2
	v_mad_u64_u32 v[146:147], s[14:15], s62, v160, 0
	v_add3_u32 v147, v147, v2, v152
	s_waitcnt lgkmcnt(0)
	v_pk_mul_f32 v[152:153], v[122:123], v[154:155] op_sel_hi:[1,0]
	v_pk_mul_f32 v[162:163], v[120:121], v[154:155] op_sel_hi:[1,0]
	v_pk_mul_f32 v[164:165], v[118:119], v[154:155] op_sel_hi:[1,0]
	v_pk_mul_f32 v[166:167], v[116:117], v[154:155] op_sel_hi:[1,0]
	v_cvt_pk_bf16_f32 v2, v162, v163
	v_cvt_pk_bf16_f32 v152, v152, v153
	v_cvt_pk_bf16_f32 v153, v166, v167
	v_cvt_pk_bf16_f32 v155, v164, v165
	ds_bpermute_b32 v162, v159, v2
	ds_bpermute_b32 v163, v159, v152
	ds_bpermute_b32 v164, v159, v153
	ds_bpermute_b32 v165, v159, v155
	v_lshl_add_u64 v[146:147], v[146:147], 1, v[150:151]
	v_pk_mul_f32 v[152:153], v[130:131], v[154:155] op_sel_hi:[1,0]
	v_pk_mul_f32 v[166:167], v[124:125], v[154:155] op_sel_hi:[1,0]
	v_cvt_pk_bf16_f32 v152, v152, v153
	s_waitcnt lgkmcnt(0)
	global_store_dwordx4 v[146:147], v[162:165], off
	v_cvt_pk_bf16_f32 v153, v166, v167
	s_mov_b64 s[14:15], 0
	v_pk_mul_f32 v[162:163], v[128:129], v[154:155] op_sel_hi:[1,0]
	v_pk_mul_f32 v[164:165], v[126:127], v[154:155] op_sel_hi:[1,0]
	v_cvt_pk_bf16_f32 v2, v162, v163
	v_cvt_pk_bf16_f32 v155, v164, v165
	ds_bpermute_b32 v162, v159, v2
	ds_bpermute_b32 v163, v159, v152
	ds_bpermute_b32 v164, v159, v153
	ds_bpermute_b32 v165, v159, v155
	s_waitcnt lgkmcnt(0)
	global_store_dwordx4 v[146:147], v[162:165], off offset:256
.LBB0_779:
	s_andn2_b64 vcc, exec, s[14:15]
	s_cbranch_vccnz .LBB0_781
	ds_read_b32 v162, v161
	ds_read_b32 v164, v161 offset:64
	ds_read_b32 v166, v161 offset:128
	ds_read_b32 v168, v161 offset:192
	ds_read_b32 v170, v161 offset:512
	ds_read_b32 v172, v161 offset:576
	ds_read_b32 v174, v161 offset:640
	ds_read_b32 v176, v161 offset:704
	s_lshl_b32 s14, s25, 5
	s_add_i32 s14, s14, s55
	s_or_b32 s14, s14, s71
	s_ashr_i32 s15, s14, 31
	s_lshl_b64 s[14:15], s[14:15], 12
	s_add_u32 s14, s73, s14
	s_addc_u32 s15, s74, s15
	s_add_u32 s14, s14, s24
	s_addc_u32 s15, s15, 0
	v_mov_b32_e32 v178, 1.0
	s_movk_i32 s16, 0x1000
	s_mov_b32 s17, 0
	v_lshl_add_u64 v[194:195], s[14:15], 0, v[148:149]
	s_waitcnt lgkmcnt(0)
	v_mul_f32_e32 v162, 0xbfb8aa3b, v162
	v_mul_f32_e32 v164, 0xbfb8aa3b, v164
	v_mul_f32_e32 v166, 0xbfb8aa3b, v166
	v_mul_f32_e32 v168, 0xbfb8aa3b, v168
	v_mul_f32_e32 v170, 0xbfb8aa3b, v170
	v_mul_f32_e32 v172, 0xbfb8aa3b, v172
	v_mul_f32_e32 v174, 0xbfb8aa3b, v174
	v_mul_f32_e32 v176, 0xbfb8aa3b, v176
	v_pk_mul_f32 v[120:121], v[120:121], v[162:163] op_sel_hi:[1,0]
	v_pk_mul_f32 v[122:123], v[122:123], v[162:163] op_sel_hi:[1,0]
	v_pk_mul_f32 v[116:117], v[116:117], v[162:163] op_sel_hi:[1,0]
	v_pk_mul_f32 v[118:119], v[118:119], v[162:163] op_sel_hi:[1,0]
	v_pk_mul_f32 v[128:129], v[128:129], v[162:163] op_sel_hi:[1,0]
	v_pk_mul_f32 v[130:131], v[130:131], v[162:163] op_sel_hi:[1,0]
	v_pk_mul_f32 v[124:125], v[124:125], v[162:163] op_sel_hi:[1,0]
	v_pk_mul_f32 v[126:127], v[126:127], v[162:163] op_sel_hi:[1,0]
	v_exp_f32_e32 v120, v120
	v_exp_f32_e32 v121, v121
	v_exp_f32_e32 v122, v122
	v_exp_f32_e32 v123, v123
	v_exp_f32_e32 v116, v116
	v_exp_f32_e32 v117, v117
	v_exp_f32_e32 v118, v118
	v_exp_f32_e32 v119, v119
	v_exp_f32_e32 v128, v128
	v_exp_f32_e32 v129, v129
	v_exp_f32_e32 v130, v130
	v_exp_f32_e32 v131, v131
	v_exp_f32_e32 v124, v124
	v_exp_f32_e32 v125, v125
	v_exp_f32_e32 v126, v126
	v_exp_f32_e32 v127, v127
	v_pk_add_f32 v[120:121], v[120:121], v[178:179] op_sel_hi:[1,0]
	v_pk_add_f32 v[122:123], v[122:123], v[178:179] op_sel_hi:[1,0]
	v_pk_add_f32 v[116:117], v[116:117], v[178:179] op_sel_hi:[1,0]
	v_pk_add_f32 v[118:119], v[118:119], v[178:179] op_sel_hi:[1,0]
	v_pk_add_f32 v[128:129], v[128:129], v[178:179] op_sel_hi:[1,0]
	v_pk_add_f32 v[130:131], v[130:131], v[178:179] op_sel_hi:[1,0]
	v_pk_add_f32 v[124:125], v[124:125], v[178:179] op_sel_hi:[1,0]
	v_pk_add_f32 v[126:127], v[126:127], v[178:179] op_sel_hi:[1,0]
	v_rcp_f32_e32 v120, v120
	v_rcp_f32_e32 v121, v121
	v_rcp_f32_e32 v122, v122
	v_rcp_f32_e32 v123, v123
	v_rcp_f32_e32 v116, v116
	v_rcp_f32_e32 v117, v117
	v_rcp_f32_e32 v118, v118
	v_rcp_f32_e32 v119, v119
	v_rcp_f32_e32 v128, v128
	v_rcp_f32_e32 v129, v129
	v_rcp_f32_e32 v130, v130
	v_rcp_f32_e32 v131, v131
	v_rcp_f32_e32 v124, v124
	v_rcp_f32_e32 v125, v125
	v_rcp_f32_e32 v126, v126
	v_rcp_f32_e32 v127, v127
	v_cvt_pk_bf16_f32 v184, v120, v121
	v_cvt_pk_bf16_f32 v185, v122, v123
	v_cvt_pk_bf16_f32 v186, v116, v117
	v_cvt_pk_bf16_f32 v187, v118, v119
	v_cvt_pk_bf16_f32 v188, v128, v129
	v_cvt_pk_bf16_f32 v189, v130, v131
	v_cvt_pk_bf16_f32 v190, v124, v125
	v_cvt_pk_bf16_f32 v191, v126, v127
	global_store_dwordx4 v[194:195], v[184:187], off
	global_store_dwordx4 v[194:195], v[188:191], off offset:1024
	v_lshl_add_u64 v[194:195], v[194:195], 0, s[16:17]
	v_pk_mul_f32 v[104:105], v[104:105], v[164:165] op_sel_hi:[1,0]
	v_pk_mul_f32 v[106:107], v[106:107], v[164:165] op_sel_hi:[1,0]
	v_pk_mul_f32 v[100:101], v[100:101], v[164:165] op_sel_hi:[1,0]
	v_pk_mul_f32 v[102:103], v[102:103], v[164:165] op_sel_hi:[1,0]
	v_pk_mul_f32 v[112:113], v[112:113], v[164:165] op_sel_hi:[1,0]
	v_pk_mul_f32 v[114:115], v[114:115], v[164:165] op_sel_hi:[1,0]
	v_pk_mul_f32 v[108:109], v[108:109], v[164:165] op_sel_hi:[1,0]
	v_pk_mul_f32 v[110:111], v[110:111], v[164:165] op_sel_hi:[1,0]
	v_exp_f32_e32 v104, v104
	v_exp_f32_e32 v105, v105
	v_exp_f32_e32 v106, v106
	v_exp_f32_e32 v107, v107
	v_exp_f32_e32 v100, v100
	v_exp_f32_e32 v101, v101
	v_exp_f32_e32 v102, v102
	v_exp_f32_e32 v103, v103
	v_exp_f32_e32 v112, v112
	v_exp_f32_e32 v113, v113
	v_exp_f32_e32 v114, v114
	v_exp_f32_e32 v115, v115
	v_exp_f32_e32 v108, v108
	v_exp_f32_e32 v109, v109
	v_exp_f32_e32 v110, v110
	v_exp_f32_e32 v111, v111
	v_pk_add_f32 v[104:105], v[104:105], v[178:179] op_sel_hi:[1,0]
	v_pk_add_f32 v[106:107], v[106:107], v[178:179] op_sel_hi:[1,0]
	v_pk_add_f32 v[100:101], v[100:101], v[178:179] op_sel_hi:[1,0]
	v_pk_add_f32 v[102:103], v[102:103], v[178:179] op_sel_hi:[1,0]
	v_pk_add_f32 v[112:113], v[112:113], v[178:179] op_sel_hi:[1,0]
	v_pk_add_f32 v[114:115], v[114:115], v[178:179] op_sel_hi:[1,0]
	v_pk_add_f32 v[108:109], v[108:109], v[178:179] op_sel_hi:[1,0]
	v_pk_add_f32 v[110:111], v[110:111], v[178:179] op_sel_hi:[1,0]
	v_rcp_f32_e32 v104, v104
	v_rcp_f32_e32 v105, v105
	v_rcp_f32_e32 v106, v106
	v_rcp_f32_e32 v107, v107
	v_rcp_f32_e32 v100, v100
	v_rcp_f32_e32 v101, v101
	v_rcp_f32_e32 v102, v102
	v_rcp_f32_e32 v103, v103
	v_rcp_f32_e32 v112, v112
	v_rcp_f32_e32 v113, v113
	v_rcp_f32_e32 v114, v114
	v_rcp_f32_e32 v115, v115
	v_rcp_f32_e32 v108, v108
	v_rcp_f32_e32 v109, v109
	v_rcp_f32_e32 v110, v110
	v_rcp_f32_e32 v111, v111
	v_cvt_pk_bf16_f32 v184, v104, v105
	v_cvt_pk_bf16_f32 v185, v106, v107
	v_cvt_pk_bf16_f32 v186, v100, v101
	v_cvt_pk_bf16_f32 v187, v102, v103
	v_cvt_pk_bf16_f32 v188, v112, v113
	v_cvt_pk_bf16_f32 v189, v114, v115
	v_cvt_pk_bf16_f32 v190, v108, v109
	v_cvt_pk_bf16_f32 v191, v110, v111
	global_store_dwordx4 v[194:195], v[184:187], off
	global_store_dwordx4 v[194:195], v[188:191], off offset:1024
	v_lshl_add_u64 v[194:195], v[194:195], 0, s[16:17]
	v_pk_mul_f32 v[88:89], v[88:89], v[166:167] op_sel_hi:[1,0]
	v_pk_mul_f32 v[90:91], v[90:91], v[166:167] op_sel_hi:[1,0]
	v_pk_mul_f32 v[84:85], v[84:85], v[166:167] op_sel_hi:[1,0]
	v_pk_mul_f32 v[86:87], v[86:87], v[166:167] op_sel_hi:[1,0]
	v_pk_mul_f32 v[96:97], v[96:97], v[166:167] op_sel_hi:[1,0]
	v_pk_mul_f32 v[98:99], v[98:99], v[166:167] op_sel_hi:[1,0]
	v_pk_mul_f32 v[92:93], v[92:93], v[166:167] op_sel_hi:[1,0]
	v_pk_mul_f32 v[94:95], v[94:95], v[166:167] op_sel_hi:[1,0]
	v_exp_f32_e32 v88, v88
	v_exp_f32_e32 v89, v89
	v_exp_f32_e32 v90, v90
	v_exp_f32_e32 v91, v91
	v_exp_f32_e32 v84, v84
	v_exp_f32_e32 v85, v85
	v_exp_f32_e32 v86, v86
	v_exp_f32_e32 v87, v87
	v_exp_f32_e32 v96, v96
	v_exp_f32_e32 v97, v97
	v_exp_f32_e32 v98, v98
	v_exp_f32_e32 v99, v99
	v_exp_f32_e32 v92, v92
	v_exp_f32_e32 v93, v93
	v_exp_f32_e32 v94, v94
	v_exp_f32_e32 v95, v95
	v_pk_add_f32 v[88:89], v[88:89], v[178:179] op_sel_hi:[1,0]
	v_pk_add_f32 v[90:91], v[90:91], v[178:179] op_sel_hi:[1,0]
	v_pk_add_f32 v[84:85], v[84:85], v[178:179] op_sel_hi:[1,0]
	v_pk_add_f32 v[86:87], v[86:87], v[178:179] op_sel_hi:[1,0]
	v_pk_add_f32 v[96:97], v[96:97], v[178:179] op_sel_hi:[1,0]
	v_pk_add_f32 v[98:99], v[98:99], v[178:179] op_sel_hi:[1,0]
	v_pk_add_f32 v[92:93], v[92:93], v[178:179] op_sel_hi:[1,0]
	v_pk_add_f32 v[94:95], v[94:95], v[178:179] op_sel_hi:[1,0]
	v_rcp_f32_e32 v88, v88
	v_rcp_f32_e32 v89, v89
	v_rcp_f32_e32 v90, v90
	v_rcp_f32_e32 v91, v91
	v_rcp_f32_e32 v84, v84
	v_rcp_f32_e32 v85, v85
	v_rcp_f32_e32 v86, v86
	v_rcp_f32_e32 v87, v87
	v_rcp_f32_e32 v96, v96
	v_rcp_f32_e32 v97, v97
	v_rcp_f32_e32 v98, v98
	v_rcp_f32_e32 v99, v99
	v_rcp_f32_e32 v92, v92
	v_rcp_f32_e32 v93, v93
	v_rcp_f32_e32 v94, v94
	v_rcp_f32_e32 v95, v95
	v_cvt_pk_bf16_f32 v184, v88, v89
	v_cvt_pk_bf16_f32 v185, v90, v91
	v_cvt_pk_bf16_f32 v186, v84, v85
	v_cvt_pk_bf16_f32 v187, v86, v87
	v_cvt_pk_bf16_f32 v188, v96, v97
	v_cvt_pk_bf16_f32 v189, v98, v99
	v_cvt_pk_bf16_f32 v190, v92, v93
	v_cvt_pk_bf16_f32 v191, v94, v95
	global_store_dwordx4 v[194:195], v[184:187], off
	global_store_dwordx4 v[194:195], v[188:191], off offset:1024
	v_lshl_add_u64 v[194:195], v[194:195], 0, s[16:17]
	v_pk_mul_f32 v[72:73], v[72:73], v[168:169] op_sel_hi:[1,0]
	v_pk_mul_f32 v[74:75], v[74:75], v[168:169] op_sel_hi:[1,0]
	v_pk_mul_f32 v[68:69], v[68:69], v[168:169] op_sel_hi:[1,0]
	v_pk_mul_f32 v[70:71], v[70:71], v[168:169] op_sel_hi:[1,0]
	v_pk_mul_f32 v[80:81], v[80:81], v[168:169] op_sel_hi:[1,0]
	v_pk_mul_f32 v[82:83], v[82:83], v[168:169] op_sel_hi:[1,0]
	v_pk_mul_f32 v[76:77], v[76:77], v[168:169] op_sel_hi:[1,0]
	v_pk_mul_f32 v[78:79], v[78:79], v[168:169] op_sel_hi:[1,0]
	v_exp_f32_e32 v72, v72
	v_exp_f32_e32 v73, v73
	v_exp_f32_e32 v74, v74
	v_exp_f32_e32 v75, v75
	v_exp_f32_e32 v68, v68
	v_exp_f32_e32 v69, v69
	v_exp_f32_e32 v70, v70
	v_exp_f32_e32 v71, v71
	v_exp_f32_e32 v80, v80
	v_exp_f32_e32 v81, v81
	v_exp_f32_e32 v82, v82
	v_exp_f32_e32 v83, v83
	v_exp_f32_e32 v76, v76
	v_exp_f32_e32 v77, v77
	v_exp_f32_e32 v78, v78
	v_exp_f32_e32 v79, v79
	v_pk_add_f32 v[72:73], v[72:73], v[178:179] op_sel_hi:[1,0]
	v_pk_add_f32 v[74:75], v[74:75], v[178:179] op_sel_hi:[1,0]
	v_pk_add_f32 v[68:69], v[68:69], v[178:179] op_sel_hi:[1,0]
	v_pk_add_f32 v[70:71], v[70:71], v[178:179] op_sel_hi:[1,0]
	v_pk_add_f32 v[80:81], v[80:81], v[178:179] op_sel_hi:[1,0]
	v_pk_add_f32 v[82:83], v[82:83], v[178:179] op_sel_hi:[1,0]
	v_pk_add_f32 v[76:77], v[76:77], v[178:179] op_sel_hi:[1,0]
	v_pk_add_f32 v[78:79], v[78:79], v[178:179] op_sel_hi:[1,0]
	v_rcp_f32_e32 v72, v72
	v_rcp_f32_e32 v73, v73
	v_rcp_f32_e32 v74, v74
	v_rcp_f32_e32 v75, v75
	v_rcp_f32_e32 v68, v68
	v_rcp_f32_e32 v69, v69
	v_rcp_f32_e32 v70, v70
	v_rcp_f32_e32 v71, v71
	v_rcp_f32_e32 v80, v80
	v_rcp_f32_e32 v81, v81
	v_rcp_f32_e32 v82, v82
	v_rcp_f32_e32 v83, v83
	v_rcp_f32_e32 v76, v76
	v_rcp_f32_e32 v77, v77
	v_rcp_f32_e32 v78, v78
	v_rcp_f32_e32 v79, v79
	v_cvt_pk_bf16_f32 v184, v72, v73
	v_cvt_pk_bf16_f32 v185, v74, v75
	v_cvt_pk_bf16_f32 v186, v68, v69
	v_cvt_pk_bf16_f32 v187, v70, v71
	v_cvt_pk_bf16_f32 v188, v80, v81
	v_cvt_pk_bf16_f32 v189, v82, v83
	v_cvt_pk_bf16_f32 v190, v76, v77
	v_cvt_pk_bf16_f32 v191, v78, v79
	global_store_dwordx4 v[194:195], v[184:187], off
	global_store_dwordx4 v[194:195], v[188:191], off offset:1024
	v_lshl_add_u64 v[194:195], v[194:195], 0, s[16:17]
	v_pk_mul_f32 v[56:57], v[56:57], v[170:171] op_sel_hi:[1,0]
	v_pk_mul_f32 v[58:59], v[58:59], v[170:171] op_sel_hi:[1,0]
	v_pk_mul_f32 v[52:53], v[52:53], v[170:171] op_sel_hi:[1,0]
	v_pk_mul_f32 v[54:55], v[54:55], v[170:171] op_sel_hi:[1,0]
	v_pk_mul_f32 v[64:65], v[64:65], v[170:171] op_sel_hi:[1,0]
	v_pk_mul_f32 v[66:67], v[66:67], v[170:171] op_sel_hi:[1,0]
	v_pk_mul_f32 v[60:61], v[60:61], v[170:171] op_sel_hi:[1,0]
	v_pk_mul_f32 v[62:63], v[62:63], v[170:171] op_sel_hi:[1,0]
	v_exp_f32_e32 v56, v56
	v_exp_f32_e32 v57, v57
	v_exp_f32_e32 v58, v58
	v_exp_f32_e32 v59, v59
	v_exp_f32_e32 v52, v52
	v_exp_f32_e32 v53, v53
	v_exp_f32_e32 v54, v54
	v_exp_f32_e32 v55, v55
	v_exp_f32_e32 v64, v64
	v_exp_f32_e32 v65, v65
	v_exp_f32_e32 v66, v66
	v_exp_f32_e32 v67, v67
	v_exp_f32_e32 v60, v60
	v_exp_f32_e32 v61, v61
	v_exp_f32_e32 v62, v62
	v_exp_f32_e32 v63, v63
	v_pk_add_f32 v[56:57], v[56:57], v[178:179] op_sel_hi:[1,0]
	v_pk_add_f32 v[58:59], v[58:59], v[178:179] op_sel_hi:[1,0]
	v_pk_add_f32 v[52:53], v[52:53], v[178:179] op_sel_hi:[1,0]
	v_pk_add_f32 v[54:55], v[54:55], v[178:179] op_sel_hi:[1,0]
	v_pk_add_f32 v[64:65], v[64:65], v[178:179] op_sel_hi:[1,0]
	v_pk_add_f32 v[66:67], v[66:67], v[178:179] op_sel_hi:[1,0]
	v_pk_add_f32 v[60:61], v[60:61], v[178:179] op_sel_hi:[1,0]
	v_pk_add_f32 v[62:63], v[62:63], v[178:179] op_sel_hi:[1,0]
	v_rcp_f32_e32 v56, v56
	v_rcp_f32_e32 v57, v57
	v_rcp_f32_e32 v58, v58
	v_rcp_f32_e32 v59, v59
	v_rcp_f32_e32 v52, v52
	v_rcp_f32_e32 v53, v53
	v_rcp_f32_e32 v54, v54
	v_rcp_f32_e32 v55, v55
	v_rcp_f32_e32 v64, v64
	v_rcp_f32_e32 v65, v65
	v_rcp_f32_e32 v66, v66
	v_rcp_f32_e32 v67, v67
	v_rcp_f32_e32 v60, v60
	v_rcp_f32_e32 v61, v61
	v_rcp_f32_e32 v62, v62
	v_rcp_f32_e32 v63, v63
	v_cvt_pk_bf16_f32 v184, v56, v57
	v_cvt_pk_bf16_f32 v185, v58, v59
	v_cvt_pk_bf16_f32 v186, v52, v53
	v_cvt_pk_bf16_f32 v187, v54, v55
	v_cvt_pk_bf16_f32 v188, v64, v65
	v_cvt_pk_bf16_f32 v189, v66, v67
	v_cvt_pk_bf16_f32 v190, v60, v61
	v_cvt_pk_bf16_f32 v191, v62, v63
	global_store_dwordx4 v[194:195], v[184:187], off
	global_store_dwordx4 v[194:195], v[188:191], off offset:1024
	v_lshl_add_u64 v[194:195], v[194:195], 0, s[16:17]
	v_pk_mul_f32 v[40:41], v[40:41], v[172:173] op_sel_hi:[1,0]
	v_pk_mul_f32 v[42:43], v[42:43], v[172:173] op_sel_hi:[1,0]
	v_pk_mul_f32 v[36:37], v[36:37], v[172:173] op_sel_hi:[1,0]
	v_pk_mul_f32 v[38:39], v[38:39], v[172:173] op_sel_hi:[1,0]
	v_pk_mul_f32 v[48:49], v[48:49], v[172:173] op_sel_hi:[1,0]
	v_pk_mul_f32 v[50:51], v[50:51], v[172:173] op_sel_hi:[1,0]
	v_pk_mul_f32 v[44:45], v[44:45], v[172:173] op_sel_hi:[1,0]
	v_pk_mul_f32 v[46:47], v[46:47], v[172:173] op_sel_hi:[1,0]
	v_exp_f32_e32 v40, v40
	v_exp_f32_e32 v41, v41
	v_exp_f32_e32 v42, v42
	v_exp_f32_e32 v43, v43
	v_exp_f32_e32 v36, v36
	v_exp_f32_e32 v37, v37
	v_exp_f32_e32 v38, v38
	v_exp_f32_e32 v39, v39
	v_exp_f32_e32 v48, v48
	v_exp_f32_e32 v49, v49
	v_exp_f32_e32 v50, v50
	v_exp_f32_e32 v51, v51
	v_exp_f32_e32 v44, v44
	v_exp_f32_e32 v45, v45
	v_exp_f32_e32 v46, v46
	v_exp_f32_e32 v47, v47
	v_pk_add_f32 v[40:41], v[40:41], v[178:179] op_sel_hi:[1,0]
	v_pk_add_f32 v[42:43], v[42:43], v[178:179] op_sel_hi:[1,0]
	v_pk_add_f32 v[36:37], v[36:37], v[178:179] op_sel_hi:[1,0]
	v_pk_add_f32 v[38:39], v[38:39], v[178:179] op_sel_hi:[1,0]
	v_pk_add_f32 v[48:49], v[48:49], v[178:179] op_sel_hi:[1,0]
	v_pk_add_f32 v[50:51], v[50:51], v[178:179] op_sel_hi:[1,0]
	v_pk_add_f32 v[44:45], v[44:45], v[178:179] op_sel_hi:[1,0]
	v_pk_add_f32 v[46:47], v[46:47], v[178:179] op_sel_hi:[1,0]
	v_rcp_f32_e32 v40, v40
	v_rcp_f32_e32 v41, v41
	v_rcp_f32_e32 v42, v42
	v_rcp_f32_e32 v43, v43
	v_rcp_f32_e32 v36, v36
	v_rcp_f32_e32 v37, v37
	v_rcp_f32_e32 v38, v38
	v_rcp_f32_e32 v39, v39
	v_rcp_f32_e32 v48, v48
	v_rcp_f32_e32 v49, v49
	v_rcp_f32_e32 v50, v50
	v_rcp_f32_e32 v51, v51
	v_rcp_f32_e32 v44, v44
	v_rcp_f32_e32 v45, v45
	v_rcp_f32_e32 v46, v46
	v_rcp_f32_e32 v47, v47
	v_cvt_pk_bf16_f32 v184, v40, v41
	v_cvt_pk_bf16_f32 v185, v42, v43
	v_cvt_pk_bf16_f32 v186, v36, v37
	v_cvt_pk_bf16_f32 v187, v38, v39
	v_cvt_pk_bf16_f32 v188, v48, v49
	v_cvt_pk_bf16_f32 v189, v50, v51
	v_cvt_pk_bf16_f32 v190, v44, v45
	v_cvt_pk_bf16_f32 v191, v46, v47
	global_store_dwordx4 v[194:195], v[184:187], off
	global_store_dwordx4 v[194:195], v[188:191], off offset:1024
	v_lshl_add_u64 v[194:195], v[194:195], 0, s[16:17]
	v_pk_mul_f32 v[24:25], v[24:25], v[174:175] op_sel_hi:[1,0]
	v_pk_mul_f32 v[26:27], v[26:27], v[174:175] op_sel_hi:[1,0]
	v_pk_mul_f32 v[20:21], v[20:21], v[174:175] op_sel_hi:[1,0]
	v_pk_mul_f32 v[22:23], v[22:23], v[174:175] op_sel_hi:[1,0]
	v_pk_mul_f32 v[32:33], v[32:33], v[174:175] op_sel_hi:[1,0]
	v_pk_mul_f32 v[34:35], v[34:35], v[174:175] op_sel_hi:[1,0]
	v_pk_mul_f32 v[28:29], v[28:29], v[174:175] op_sel_hi:[1,0]
	v_pk_mul_f32 v[30:31], v[30:31], v[174:175] op_sel_hi:[1,0]
	v_exp_f32_e32 v24, v24
	v_exp_f32_e32 v25, v25
	v_exp_f32_e32 v26, v26
	v_exp_f32_e32 v27, v27
	v_exp_f32_e32 v20, v20
	v_exp_f32_e32 v21, v21
	v_exp_f32_e32 v22, v22
	v_exp_f32_e32 v23, v23
	v_exp_f32_e32 v32, v32
	v_exp_f32_e32 v33, v33
	v_exp_f32_e32 v34, v34
	v_exp_f32_e32 v35, v35
	v_exp_f32_e32 v28, v28
	v_exp_f32_e32 v29, v29
	v_exp_f32_e32 v30, v30
	v_exp_f32_e32 v31, v31
	v_pk_add_f32 v[24:25], v[24:25], v[178:179] op_sel_hi:[1,0]
	v_pk_add_f32 v[26:27], v[26:27], v[178:179] op_sel_hi:[1,0]
	v_pk_add_f32 v[20:21], v[20:21], v[178:179] op_sel_hi:[1,0]
	v_pk_add_f32 v[22:23], v[22:23], v[178:179] op_sel_hi:[1,0]
	v_pk_add_f32 v[32:33], v[32:33], v[178:179] op_sel_hi:[1,0]
	v_pk_add_f32 v[34:35], v[34:35], v[178:179] op_sel_hi:[1,0]
	v_pk_add_f32 v[28:29], v[28:29], v[178:179] op_sel_hi:[1,0]
	v_pk_add_f32 v[30:31], v[30:31], v[178:179] op_sel_hi:[1,0]
	v_rcp_f32_e32 v24, v24
	v_rcp_f32_e32 v25, v25
	v_rcp_f32_e32 v26, v26
	v_rcp_f32_e32 v27, v27
	v_rcp_f32_e32 v20, v20
	v_rcp_f32_e32 v21, v21
	v_rcp_f32_e32 v22, v22
	v_rcp_f32_e32 v23, v23
	v_rcp_f32_e32 v32, v32
	v_rcp_f32_e32 v33, v33
	v_rcp_f32_e32 v34, v34
	v_rcp_f32_e32 v35, v35
	v_rcp_f32_e32 v28, v28
	v_rcp_f32_e32 v29, v29
	v_rcp_f32_e32 v30, v30
	v_rcp_f32_e32 v31, v31
	v_cvt_pk_bf16_f32 v184, v24, v25
	v_cvt_pk_bf16_f32 v185, v26, v27
	v_cvt_pk_bf16_f32 v186, v20, v21
	v_cvt_pk_bf16_f32 v187, v22, v23
	v_cvt_pk_bf16_f32 v188, v32, v33
	v_cvt_pk_bf16_f32 v189, v34, v35
	v_cvt_pk_bf16_f32 v190, v28, v29
	v_cvt_pk_bf16_f32 v191, v30, v31
	global_store_dwordx4 v[194:195], v[184:187], off
	global_store_dwordx4 v[194:195], v[188:191], off offset:1024
	v_lshl_add_u64 v[194:195], v[194:195], 0, s[16:17]
	v_pk_mul_f32 v[8:9], v[8:9], v[176:177] op_sel_hi:[1,0]
	v_pk_mul_f32 v[10:11], v[10:11], v[176:177] op_sel_hi:[1,0]
	v_pk_mul_f32 v[4:5], v[4:5], v[176:177] op_sel_hi:[1,0]
	v_pk_mul_f32 v[6:7], v[6:7], v[176:177] op_sel_hi:[1,0]
	v_pk_mul_f32 v[16:17], v[16:17], v[176:177] op_sel_hi:[1,0]
	v_pk_mul_f32 v[18:19], v[18:19], v[176:177] op_sel_hi:[1,0]
	v_pk_mul_f32 v[12:13], v[12:13], v[176:177] op_sel_hi:[1,0]
	v_pk_mul_f32 v[14:15], v[14:15], v[176:177] op_sel_hi:[1,0]
	v_exp_f32_e32 v8, v8
	v_exp_f32_e32 v9, v9
	v_exp_f32_e32 v10, v10
	v_exp_f32_e32 v11, v11
	v_exp_f32_e32 v4, v4
	v_exp_f32_e32 v5, v5
	v_exp_f32_e32 v6, v6
	v_exp_f32_e32 v7, v7
	v_exp_f32_e32 v16, v16
	v_exp_f32_e32 v17, v17
	v_exp_f32_e32 v18, v18
	v_exp_f32_e32 v19, v19
	v_exp_f32_e32 v12, v12
	v_exp_f32_e32 v13, v13
	v_exp_f32_e32 v14, v14
	v_exp_f32_e32 v15, v15
	v_pk_add_f32 v[8:9], v[8:9], v[178:179] op_sel_hi:[1,0]
	v_pk_add_f32 v[10:11], v[10:11], v[178:179] op_sel_hi:[1,0]
	v_pk_add_f32 v[4:5], v[4:5], v[178:179] op_sel_hi:[1,0]
	v_pk_add_f32 v[6:7], v[6:7], v[178:179] op_sel_hi:[1,0]
	v_pk_add_f32 v[16:17], v[16:17], v[178:179] op_sel_hi:[1,0]
	v_pk_add_f32 v[18:19], v[18:19], v[178:179] op_sel_hi:[1,0]
	v_pk_add_f32 v[12:13], v[12:13], v[178:179] op_sel_hi:[1,0]
	v_pk_add_f32 v[14:15], v[14:15], v[178:179] op_sel_hi:[1,0]
	v_rcp_f32_e32 v8, v8
	v_rcp_f32_e32 v9, v9
	v_rcp_f32_e32 v10, v10
	v_rcp_f32_e32 v11, v11
	v_rcp_f32_e32 v4, v4
	v_rcp_f32_e32 v5, v5
	v_rcp_f32_e32 v6, v6
	v_rcp_f32_e32 v7, v7
	v_rcp_f32_e32 v16, v16
	v_rcp_f32_e32 v17, v17
	v_rcp_f32_e32 v18, v18
	v_rcp_f32_e32 v19, v19
	v_rcp_f32_e32 v12, v12
	v_rcp_f32_e32 v13, v13
	v_rcp_f32_e32 v14, v14
	v_rcp_f32_e32 v15, v15
	v_cvt_pk_bf16_f32 v184, v8, v9
	v_cvt_pk_bf16_f32 v185, v10, v11
	v_cvt_pk_bf16_f32 v186, v4, v5
	v_cvt_pk_bf16_f32 v187, v6, v7
	v_cvt_pk_bf16_f32 v188, v16, v17
	v_cvt_pk_bf16_f32 v189, v18, v19
	v_cvt_pk_bf16_f32 v190, v12, v13
	v_cvt_pk_bf16_f32 v191, v14, v15
	global_store_dwordx4 v[194:195], v[184:187], off
	global_store_dwordx4 v[194:195], v[188:191], off offset:1024
	s_branch .LBB0_860
	s_waitcnt lgkmcnt(0)
	v_pk_mul_f32 v[164:165], v[116:117], v[154:155] op_sel_hi:[1,0]
	v_pk_mul_f32 v[152:153], v[122:123], v[154:155] op_sel_hi:[1,0]
	v_pk_mul_f32 v[162:163], v[120:121], v[154:155] op_sel_hi:[1,0]
	v_mul_f32_e32 v155, 0xbfb8aa3b, v164
	v_exp_f32_e32 v155, v155
	v_mul_f32_e32 v2, 0xbfb8aa3b, v162
	v_mul_f32_e32 v162, 0xbfb8aa3b, v163
	v_exp_f32_e32 v2, v2
	v_exp_f32_e32 v162, v162
	v_pk_mul_f32 v[166:167], v[118:119], v[154:155] op_sel_hi:[1,0]
	v_add_f32_e32 v155, 1.0, v155
	v_rcp_f32_e32 v155, v155
	v_add_f32_e32 v2, 1.0, v2
	v_add_f32_e32 v162, 1.0, v162
	v_rcp_f32_e32 v2, v2
	v_rcp_f32_e32 v162, v162
	v_pk_mul_f32 v[124:125], v[124:125], v[154:155] op_sel_hi:[1,0]
	v_pk_mul_f32 v[128:129], v[128:129], v[154:155] op_sel_hi:[1,0]
	v_mul_f32_e32 v124, 0xbfb8aa3b, v124
	v_cvt_pk_bf16_f32 v162, v2, v162
	v_mul_f32_e32 v2, 0xbfb8aa3b, v128
	v_exp_f32_e32 v124, v124
	v_mul_f32_e32 v128, 0xbfb8aa3b, v129
	v_exp_f32_e32 v128, v128
	v_mul_f32_e32 v163, 0xbfb8aa3b, v165
	v_pk_mul_f32 v[130:131], v[130:131], v[154:155] op_sel_hi:[1,0]
	v_add_f32_e32 v124, 1.0, v124
	v_mul_f32_e32 v125, 0xbfb8aa3b, v125
	v_exp_f32_e32 v163, v163
	v_mul_f32_e32 v164, 0xbfb8aa3b, v166
	v_exp_f32_e32 v125, v125
	v_rcp_f32_e32 v129, v124
	v_add_f32_e32 v124, 1.0, v128
	v_mul_f32_e32 v128, 0xbfb8aa3b, v130
	v_exp_f32_e32 v164, v164
	v_exp_f32_e32 v128, v128
	v_pk_mul_f32 v[126:127], v[126:127], v[154:155] op_sel_hi:[1,0]
	v_add_f32_e32 v163, 1.0, v163
	v_add_f32_e32 v125, 1.0, v125
	v_mul_f32_e32 v126, 0xbfb8aa3b, v126
	v_mul_f32_e32 v152, 0xbfb8aa3b, v152
	v_rcp_f32_e32 v165, v163
	v_add_f32_e32 v163, 1.0, v164
	v_mul_f32_e32 v153, 0xbfb8aa3b, v153
	v_mul_f32_e32 v164, 0xbfb8aa3b, v167
	v_exp_f32_e32 v126, v126
	v_rcp_f32_e32 v130, v125
	v_add_f32_e32 v125, 1.0, v128
	v_mul_f32_e32 v128, 0xbfb8aa3b, v131
	v_mul_f32_e32 v127, 0xbfb8aa3b, v127
	s_lshl_b32 s14, s25, 5
	v_exp_f32_e32 v152, v152
	v_exp_f32_e32 v153, v153
	v_exp_f32_e32 v164, v164
	v_exp_f32_e32 v2, v2
	v_exp_f32_e32 v128, v128
	v_exp_f32_e32 v127, v127
	s_add_i32 s14, s14, s55
	s_or_b32 s14, s14, s71
	s_ashr_i32 s15, s14, 31
	v_add_f32_e32 v126, 1.0, v126
	s_lshl_b64 s[14:15], s[14:15], 12
	v_add_f32_e32 v152, 1.0, v152
	v_rcp_f32_e32 v166, v163
	v_add_f32_e32 v153, 1.0, v153
	v_add_f32_e32 v163, 1.0, v164
	v_add_f32_e32 v2, 1.0, v2
	v_rcp_f32_e32 v131, v126
	v_add_f32_e32 v126, 1.0, v128
	v_add_f32_e32 v127, 1.0, v127
	s_add_u32 s14, s73, s14
	v_rcp_f32_e32 v152, v152
	v_rcp_f32_e32 v153, v153
	v_rcp_f32_e32 v167, v163
	v_rcp_f32_e32 v2, v2
	v_rcp_f32_e32 v124, v124
	v_rcp_f32_e32 v125, v125
	v_rcp_f32_e32 v126, v126
	v_rcp_f32_e32 v127, v127
	s_addc_u32 s15, s74, s15
	s_add_u32 s14, s14, s24
	s_addc_u32 s15, s15, 0
	v_lshl_add_u64 v[146:147], s[14:15], 0, v[148:149]
	v_cvt_pk_bf16_f32 v163, v152, v153
	v_cvt_pk_bf16_f32 v164, v155, v165
	v_cvt_pk_bf16_f32 v165, v166, v167
	v_cvt_pk_bf16_f32 v124, v2, v124
	v_cvt_pk_bf16_f32 v125, v125, v126
	v_cvt_pk_bf16_f32 v126, v129, v130
	v_cvt_pk_bf16_f32 v127, v131, v127
	global_store_dwordx4 v[146:147], v[162:165], off
	global_store_dwordx4 v[146:147], v[124:127], off offset:1024
